# attention last KV tile: V-fragment LDS reads issued 6 deep with counted lgkmcnt (was 16 serialized read-wait-MFMA steps)
# baseline (speedup 1.0000x reference)
.LBB0_591:
	v_sub_f32_e32 v2, v80, v4
	v_sub_f32_e32 v5, v96, v4
	v_exp_f32_e32 v2, v2
	v_exp_f32_e32 v5, v5
	v_sub_f32_e32 v7, v81, v4
	v_sub_f32_e32 v8, v97, v4
	v_exp_f32_e32 v7, v7
	v_exp_f32_e32 v10, v8
	v_add_f32_e32 v6, v2, v5
	v_add_f32_e32 v6, 0, v6
	v_sub_f32_e32 v9, v98, v4
	v_add_f32_e32 v8, v7, v10
	v_add_f32_e32 v6, v8, v6
	v_sub_f32_e32 v8, v82, v4
	v_exp_f32_e32 v8, v8
	v_exp_f32_e32 v11, v9
	v_sub_f32_e32 v12, v99, v4
	v_exp_f32_e32 v12, v12
	v_sub_f32_e32 v15, v100, v4
	v_add_f32_e32 v9, v8, v11
	v_add_f32_e32 v6, v9, v6
	v_sub_f32_e32 v9, v83, v4
	v_exp_f32_e32 v9, v9
	v_exp_f32_e32 v15, v15
	v_sub_f32_e32 v81, v101, v4
	v_exp_f32_e32 v81, v81
	v_add_f32_e32 v13, v9, v12
	v_add_f32_e32 v6, v13, v6
	v_sub_f32_e32 v13, v84, v4
	v_exp_f32_e32 v13, v13
	v_sub_f32_e32 v83, v102, v4
	v_exp_f32_e32 v83, v83
	v_sub_f32_e32 v90, v90, v4
	v_add_f32_e32 v80, v13, v15
	v_add_f32_e32 v6, v80, v6
	v_sub_f32_e32 v80, v85, v4
	v_exp_f32_e32 v80, v80
	v_sub_f32_e32 v85, v103, v4
	v_exp_f32_e32 v85, v85
	v_exp_f32_e32 v90, v90
	v_add_f32_e32 v82, v80, v81
	v_add_f32_e32 v6, v82, v6
	v_sub_f32_e32 v82, v86, v4
	v_exp_f32_e32 v82, v82
	v_sub_f32_e32 v91, v91, v4
	v_exp_f32_e32 v91, v91
	v_sub_f32_e32 v92, v92, v4
	v_add_f32_e32 v84, v82, v83
	v_add_f32_e32 v6, v84, v6
	v_sub_f32_e32 v84, v87, v4
	v_exp_f32_e32 v84, v84
	v_sub_f32_e32 v87, v104, v4
	v_exp_f32_e32 v87, v87
	v_exp_f32_e32 v92, v92
	v_add_f32_e32 v86, v84, v85
	v_add_f32_e32 v6, v86, v6
	v_sub_f32_e32 v86, v88, v4
	v_exp_f32_e32 v86, v86
	v_sub_f32_e32 v93, v93, v4
	v_exp_f32_e32 v93, v93
	v_sub_f32_e32 v94, v94, v4
	v_add_f32_e32 v88, v86, v87
	v_add_f32_e32 v6, v88, v6
	v_sub_f32_e32 v88, v89, v4
	v_sub_f32_e32 v89, v105, v4
	v_exp_f32_e32 v88, v88
	v_exp_f32_e32 v89, v89
	v_exp_f32_e32 v94, v94
	v_sub_f32_e32 v95, v95, v4
	v_exp_f32_e32 v95, v95
	v_add_f32_e32 v96, v88, v89
	v_add_f32_e32 v6, v96, v6
	v_sub_f32_e32 v96, v106, v4
	v_exp_f32_e32 v96, v96
	v_add_u32_e32 v14, s18, v218
	s_lshl_b64 s[2:3], s[2:3], 11
	s_add_u32 s2, s31, s2
	v_add_f32_e32 v97, v90, v96
	v_add_f32_e32 v6, v97, v6
	v_sub_f32_e32 v97, v107, v4
	v_exp_f32_e32 v97, v97
	s_addc_u32 s3, s34, s3
	v_add_f32_e32 v98, v91, v97
	v_add_f32_e32 v6, v98, v6
	v_sub_f32_e32 v98, v108, v4
	v_exp_f32_e32 v98, v98
	s_nop 0
	v_add_f32_e32 v99, v92, v98
	v_add_f32_e32 v6, v99, v6
	v_sub_f32_e32 v99, v109, v4
	v_exp_f32_e32 v99, v99
	s_nop 0
	v_add_f32_e32 v100, v93, v99
	v_add_f32_e32 v6, v100, v6
	v_sub_f32_e32 v100, v110, v4
	v_exp_f32_e32 v100, v100
	v_sub_f32_e32 v4, v111, v4
	v_add_f32_e32 v101, v94, v100
	v_add_f32_e32 v6, v101, v6
	v_exp_f32_e32 v101, v4
	s_nop 0
	v_add_f32_e32 v4, v95, v101
	v_add_f32_e32 v102, v4, v6
	v_fmac_f32_e32 v102, v3, v0
	v_add_u32_e32 v0, s19, v217
	v_cvt_pk_bf16_f32 v6, v2, v7
	v_cvt_pk_bf16_f32 v7, v8, v9
	v_cvt_pk_bf16_f32 v8, v13, v80
	v_cvt_pk_bf16_f32 v9, v82, v84
	v_cvt_pk_bf16_f32 v10, v5, v10
	v_cvt_pk_bf16_f32 v11, v11, v12
	v_cvt_pk_bf16_f32 v12, v15, v81
	v_cvt_pk_bf16_f32 v13, v83, v85
	v_cvt_pk_bf16_f32 v80, v86, v88
	v_cvt_pk_bf16_f32 v81, v90, v91
	v_cvt_pk_bf16_f32 v82, v92, v93
	v_cvt_pk_bf16_f32 v83, v94, v95
	v_cvt_pk_bf16_f32 v2, v87, v89
	v_cvt_pk_bf16_f32 v3, v96, v97
	v_cvt_pk_bf16_f32 v4, v98, v99
	v_cvt_pk_bf16_f32 v5, v100, v101
	v_xad_u32 v100, v14, 32, 0
	v_xad_u32 v101, v14, 64, 0
	v_xor_b32_e32 v103, 0x60, v14
	v_add_u32_e32 v103, 0, v103
	ds_read_b128 v[84:87], v0 offset:24576
	ds_read_b128 v[88:91], v0 offset:28672
	ds_read_b128 v[92:95], v0 offset:32768
	ds_read_b128 v[96:99], v0 offset:36864
	ds_read_b128 v[104:107], v100
	ds_read_b128 v[108:111], v100 offset:4096
	s_waitcnt lgkmcnt(5)
	v_mfma_f32_32x32x16_bf16 v[64:79], v[84:87], v[6:9], v[64:79]
	ds_read_b128 v[84:87], v100 offset:8192
	s_waitcnt lgkmcnt(5)
	v_mfma_f32_32x32x16_bf16 v[48:63], v[88:91], v[6:9], v[48:63]
	ds_read_b128 v[88:91], v100 offset:12288
	s_waitcnt lgkmcnt(5)
	v_mfma_f32_32x32x16_bf16 v[32:47], v[92:95], v[6:9], v[32:47]
	ds_read_b128 v[92:95], v101
	s_waitcnt lgkmcnt(5)
	v_mfma_f32_32x32x16_bf16 v[16:31], v[96:99], v[6:9], v[16:31]
	ds_read_b128 v[96:99], v101 offset:4096
	s_waitcnt lgkmcnt(5)
	v_mfma_f32_32x32x16_bf16 v[64:79], v[104:107], v[80:83], v[64:79]
	ds_read_b128 v[104:107], v101 offset:8192
	s_waitcnt lgkmcnt(5)
	v_mfma_f32_32x32x16_bf16 v[48:63], v[108:111], v[80:83], v[48:63]
	ds_read_b128 v[108:111], v101 offset:12288
	s_waitcnt lgkmcnt(5)
	v_mfma_f32_32x32x16_bf16 v[32:47], v[84:87], v[80:83], v[32:47]
	ds_read_b128 v[84:87], v103
	s_waitcnt lgkmcnt(5)
	v_mfma_f32_32x32x16_bf16 v[16:31], v[88:91], v[80:83], v[16:31]
	ds_read_b128 v[88:91], v103 offset:4096
	s_waitcnt lgkmcnt(5)
	v_mfma_f32_32x32x16_bf16 v[64:79], v[92:95], v[10:13], v[64:79]
	ds_read_b128 v[92:95], v103 offset:8192
	s_waitcnt lgkmcnt(5)
	v_mfma_f32_32x32x16_bf16 v[48:63], v[96:99], v[10:13], v[48:63]
	ds_read_b128 v[96:99], v103 offset:12288
	s_waitcnt lgkmcnt(5)
	v_mfma_f32_32x32x16_bf16 v[32:47], v[104:107], v[10:13], v[32:47]
	ds_bpermute_b32 v0, v219, v102
	s_waitcnt lgkmcnt(5)
	v_mfma_f32_32x32x16_bf16 v[16:31], v[108:111], v[10:13], v[16:31]
	s_waitcnt lgkmcnt(4)
	v_mfma_f32_32x32x16_bf16 v[64:79], v[84:87], v[2:5], v[64:79]
	s_waitcnt lgkmcnt(3)
	v_mfma_f32_32x32x16_bf16 v[48:63], v[88:91], v[2:5], v[48:63]
	s_waitcnt lgkmcnt(2)
	v_mfma_f32_32x32x16_bf16 v[32:47], v[92:95], v[2:5], v[32:47]
	s_waitcnt lgkmcnt(1)
	v_mfma_f32_32x32x16_bf16 v[16:31], v[96:99], v[2:5], v[16:31]
	s_waitcnt lgkmcnt(0)
	v_add_f32_e32 v0, v102, v0
	v_div_scale_f32 v2, s[18:19], v0, v0, 1.0
	v_rcp_f32_e32 v3, v2
	s_lshl_b32 s18, s42, 1
	s_add_u32 s2, s2, s18
	s_addc_u32 s3, s3, 0
	v_fma_f32 v4, -v2, v3, 1.0
	v_fmac_f32_e32 v3, v4, v3
	v_div_scale_f32 v4, vcc, 1.0, v0, 1.0
	v_mul_f32_e32 v5, v4, v3
	v_fma_f32 v6, -v2, v5, v4
	v_fmac_f32_e32 v5, v6, v3
	v_fma_f32 v2, -v2, v5, v4
	v_div_fmas_f32 v2, v2, v3, v5
	v_div_fixup_f32 v0, v2, v0, 1.0
	v_and_b32_e32 v10, 32, v179
	v_lshrrev_b32_e32 v10, 2, v10
	v_add_u32_e32 v10, v172, v10
	v_mov_b32_e32 v11, v1
	v_lshl_add_u64 v[2:3], s[2:3], 0, v[10:11]
	v_mul_f32_e32 v8, v64, v0
	v_mul_f32_e32 v9, v65, v0
	v_cvt_pk_bf16_f32 v4, v8, v9
	v_mul_f32_e32 v8, v66, v0
	v_mul_f32_e32 v9, v67, v0
	v_cvt_pk_bf16_f32 v5, v8, v9
	v_mul_f32_e32 v8, v68, v0
	v_mul_f32_e32 v9, v69, v0
	v_cvt_pk_bf16_f32 v6, v8, v9
	v_mul_f32_e32 v8, v70, v0
	v_mul_f32_e32 v9, v71, v0
	v_cvt_pk_bf16_f32 v7, v8, v9
	s_nop 1
	v_permlane32_swap_b32_e32 v4, v6
	v_permlane32_swap_b32_e32 v5, v7
	global_store_dwordx4 v[2:3], v[4:7], off
	v_mul_f32_e32 v8, v72, v0
	v_mul_f32_e32 v9, v73, v0
	v_cvt_pk_bf16_f32 v4, v8, v9
	v_mul_f32_e32 v8, v74, v0
	v_mul_f32_e32 v9, v75, v0
	v_cvt_pk_bf16_f32 v5, v8, v9
	v_mul_f32_e32 v8, v76, v0
	v_mul_f32_e32 v9, v77, v0
	v_cvt_pk_bf16_f32 v6, v8, v9
	v_mul_f32_e32 v8, v78, v0
	v_mul_f32_e32 v9, v79, v0
	v_cvt_pk_bf16_f32 v7, v8, v9
	s_nop 1
	v_permlane32_swap_b32_e32 v4, v6
	v_permlane32_swap_b32_e32 v5, v7
	global_store_dwordx4 v[2:3], v[4:7], off offset:32
	v_mul_f32_e32 v8, v48, v0
	v_mul_f32_e32 v9, v49, v0
	v_cvt_pk_bf16_f32 v4, v8, v9
	v_mul_f32_e32 v8, v50, v0
	v_mul_f32_e32 v9, v51, v0
	v_cvt_pk_bf16_f32 v5, v8, v9
	v_mul_f32_e32 v8, v52, v0
	v_mul_f32_e32 v9, v53, v0
	v_cvt_pk_bf16_f32 v6, v8, v9
	v_mul_f32_e32 v8, v54, v0
	v_mul_f32_e32 v9, v55, v0
	v_cvt_pk_bf16_f32 v7, v8, v9
	s_nop 1
	v_permlane32_swap_b32_e32 v4, v6
	v_permlane32_swap_b32_e32 v5, v7
	global_store_dwordx4 v[2:3], v[4:7], off offset:64
	v_mul_f32_e32 v8, v56, v0
	v_mul_f32_e32 v9, v57, v0
	v_cvt_pk_bf16_f32 v4, v8, v9
	v_mul_f32_e32 v8, v58, v0
	v_mul_f32_e32 v9, v59, v0
	v_cvt_pk_bf16_f32 v5, v8, v9
	v_mul_f32_e32 v8, v60, v0
	v_mul_f32_e32 v9, v61, v0
	v_cvt_pk_bf16_f32 v6, v8, v9
	v_mul_f32_e32 v8, v62, v0
	v_mul_f32_e32 v9, v63, v0
	v_cvt_pk_bf16_f32 v7, v8, v9
	s_nop 1
	v_permlane32_swap_b32_e32 v4, v6
	v_permlane32_swap_b32_e32 v5, v7
	global_store_dwordx4 v[2:3], v[4:7], off offset:96
	v_mul_f32_e32 v8, v32, v0
	v_mul_f32_e32 v9, v33, v0
	v_cvt_pk_bf16_f32 v4, v8, v9
	v_mul_f32_e32 v8, v34, v0
	v_mul_f32_e32 v9, v35, v0
	v_cvt_pk_bf16_f32 v5, v8, v9
	v_mul_f32_e32 v8, v36, v0
	v_mul_f32_e32 v9, v37, v0
	v_cvt_pk_bf16_f32 v6, v8, v9
	v_mul_f32_e32 v8, v38, v0
	v_mul_f32_e32 v9, v39, v0
	v_cvt_pk_bf16_f32 v7, v8, v9
	s_nop 1
	v_permlane32_swap_b32_e32 v4, v6
	v_permlane32_swap_b32_e32 v5, v7
	global_store_dwordx4 v[2:3], v[4:7], off offset:128
	v_mul_f32_e32 v8, v40, v0
	v_mul_f32_e32 v9, v41, v0
	v_cvt_pk_bf16_f32 v4, v8, v9
	v_mul_f32_e32 v8, v42, v0
	v_mul_f32_e32 v9, v43, v0
	v_cvt_pk_bf16_f32 v5, v8, v9
	v_mul_f32_e32 v8, v44, v0
	v_mul_f32_e32 v9, v45, v0
	v_cvt_pk_bf16_f32 v6, v8, v9
	v_mul_f32_e32 v8, v46, v0
	v_mul_f32_e32 v9, v47, v0
	v_cvt_pk_bf16_f32 v7, v8, v9
	s_nop 1
	v_permlane32_swap_b32_e32 v4, v6
	v_permlane32_swap_b32_e32 v5, v7
	global_store_dwordx4 v[2:3], v[4:7], off offset:160
	v_mul_f32_e32 v8, v16, v0
	v_mul_f32_e32 v9, v17, v0
	v_cvt_pk_bf16_f32 v4, v8, v9
	v_mul_f32_e32 v8, v18, v0
	v_mul_f32_e32 v9, v19, v0
	v_cvt_pk_bf16_f32 v5, v8, v9
	v_mul_f32_e32 v8, v20, v0
	v_mul_f32_e32 v9, v21, v0
	v_cvt_pk_bf16_f32 v6, v8, v9
	v_mul_f32_e32 v8, v22, v0
	v_mul_f32_e32 v9, v23, v0
	v_cvt_pk_bf16_f32 v7, v8, v9
	s_nop 1
	v_permlane32_swap_b32_e32 v4, v6
	v_permlane32_swap_b32_e32 v5, v7
	global_store_dwordx4 v[2:3], v[4:7], off offset:192
	v_mul_f32_e32 v8, v24, v0
	v_mul_f32_e32 v9, v25, v0
	v_cvt_pk_bf16_f32 v4, v8, v9
	v_mul_f32_e32 v8, v26, v0
	v_mul_f32_e32 v9, v27, v0
	v_cvt_pk_bf16_f32 v5, v8, v9
	v_mul_f32_e32 v8, v28, v0
	v_mul_f32_e32 v9, v29, v0
	v_cvt_pk_bf16_f32 v6, v8, v9
	v_mul_f32_e32 v8, v30, v0
	v_mul_f32_e32 v9, v31, v0
	v_cvt_pk_bf16_f32 v7, v8, v9
	s_nop 1
	v_permlane32_swap_b32_e32 v4, v6
	v_permlane32_swap_b32_e32 v5, v7
	global_store_dwordx4 v[2:3], v[4:7], off offset:224
	s_add_i32 s16, s16, s64
	s_cmpk_gt_i32 s16, 0x27f
	s_cbranch_scc1 .LBB0_605
